# attention unit epilogue tail: gate and norm-weight loads hoisted to the first consumption point into dead loop registers, exact counted waits
# speedup vs baseline: 1.0017x; 1.0013x over previous
.LBB0_527:
	ds_bpermute_b32 v16, v221, v193
	s_waitcnt lgkmcnt(0)
	s_barrier
	s_mov_b32 s15, 0x800000
	s_waitcnt lgkmcnt(0)
	v_add_f32_e32 v16, v193, v16
	v_div_scale_f32 v17, s[16:17], v16, v16, 1.0
	v_rcp_f32_e32 v18, v17
	v_div_scale_f32 v19, vcc, 1.0, v16, 1.0
	v_fma_f32 v20, -v17, v18, 1.0
	v_fmac_f32_e32 v18, v20, v18
	v_mul_f32_e32 v20, v19, v18
	v_fma_f32 v21, -v17, v20, v19
	v_fmac_f32_e32 v20, v21, v18
	v_fma_f32 v17, -v17, v20, v19
	v_div_fmas_f32 v17, v17, v18, v20
	v_div_fixup_f32 v20, v17, v16, 1.0
	v_cndmask_b32_e64 v16, 0, 1, s[6:7]
	v_cmp_ne_u32_e64 s[72:73], 1, v16
	s_andn2_b64 vcc, exec, s[6:7]
	s_mov_b64 s[6:7], -1
	s_cbranch_vccnz .LBB0_529
	ds_read2st64_b32 v[16:17], v209 offset0:224 offset1:225
	ds_read2st64_b32 v[18:19], v209 offset0:226 offset1:227
	ds_read2st64_b32 v[22:23], v209 offset0:228 offset1:229
	ds_read2st64_b32 v[24:25], v209 offset0:230 offset1:231
	v_pk_mul_f32 v[64:65], v[130:131], v[20:21] op_sel_hi:[1,0]
	s_waitcnt lgkmcnt(3)
	v_lshlrev_b32_e32 v36, 16, v16
	v_and_b32_e32 v37, 0xffff0000, v16
	v_lshlrev_b32_e32 v38, 16, v17
	v_and_b32_e32 v39, 0xffff0000, v17
	ds_read2st64_b32 v[16:17], v209 offset0:232 offset1:233
	s_waitcnt lgkmcnt(3)
	v_lshlrev_b32_e32 v40, 16, v18
	v_and_b32_e32 v41, 0xffff0000, v18
	v_lshlrev_b32_e32 v42, 16, v19
	v_and_b32_e32 v43, 0xffff0000, v19
	s_waitcnt lgkmcnt(2)
	v_lshlrev_b32_e32 v44, 16, v22
	v_and_b32_e32 v45, 0xffff0000, v22
	v_lshlrev_b32_e32 v46, 16, v23
	v_and_b32_e32 v47, 0xffff0000, v23
	s_waitcnt lgkmcnt(1)
	v_lshlrev_b32_e32 v48, 16, v24
	v_and_b32_e32 v49, 0xffff0000, v24
	v_lshlrev_b32_e32 v50, 16, v25
	v_and_b32_e32 v51, 0xffff0000, v25
	ds_read2st64_b32 v[18:19], v209 offset0:234 offset1:235
	ds_read2st64_b32 v[22:23], v209 offset0:236 offset1:237
	ds_read2st64_b32 v[24:25], v209 offset0:238 offset1:239
	s_waitcnt lgkmcnt(3)
	v_lshlrev_b32_e32 v52, 16, v16
	v_and_b32_e32 v53, 0xffff0000, v16
	v_lshlrev_b32_e32 v54, 16, v17
	v_and_b32_e32 v55, 0xffff0000, v17
	ds_read2st64_b32 v[16:17], v209 offset0:240 offset1:241
	s_waitcnt lgkmcnt(3)
	v_lshlrev_b32_e32 v56, 16, v18
	v_and_b32_e32 v57, 0xffff0000, v18
	v_lshlrev_b32_e32 v58, 16, v19
	v_and_b32_e32 v59, 0xffff0000, v19
	s_waitcnt lgkmcnt(2)
	v_lshlrev_b32_e32 v62, 16, v22
	v_and_b32_e32 v63, 0xffff0000, v22
	v_lshlrev_b32_e32 v60, 16, v23
	v_and_b32_e32 v61, 0xffff0000, v23
	s_waitcnt lgkmcnt(1)
	v_lshlrev_b32_e32 v156, 16, v24
	v_and_b32_e32 v157, 0xffff0000, v24
	v_lshlrev_b32_e32 v158, 16, v25
	v_and_b32_e32 v159, 0xffff0000, v25
	ds_read2st64_b32 v[18:19], v209 offset0:242 offset1:243
	ds_read2st64_b32 v[22:23], v209 offset0:244 offset1:245
	ds_read2st64_b32 v[24:25], v209 offset0:246 offset1:247
	s_waitcnt lgkmcnt(3)
	v_lshlrev_b32_e32 v160, 16, v16
	v_and_b32_e32 v161, 0xffff0000, v16
	v_lshlrev_b32_e32 v162, 16, v17
	v_and_b32_e32 v163, 0xffff0000, v17
	ds_read2st64_b32 v[16:17], v209 offset0:248 offset1:249
	s_waitcnt lgkmcnt(3)
	v_lshlrev_b32_e32 v164, 16, v18
	v_and_b32_e32 v165, 0xffff0000, v18
	v_lshlrev_b32_e32 v166, 16, v19
	v_and_b32_e32 v167, 0xffff0000, v19
	s_waitcnt lgkmcnt(2)
	v_lshlrev_b32_e32 v168, 16, v22
	v_and_b32_e32 v169, 0xffff0000, v22
	v_lshlrev_b32_e32 v170, 16, v23
	v_and_b32_e32 v171, 0xffff0000, v23
	s_waitcnt lgkmcnt(1)
	v_lshlrev_b32_e32 v30, 16, v24
	v_and_b32_e32 v31, 0xffff0000, v24
	v_lshlrev_b32_e32 v192, 16, v25
	v_and_b32_e32 v193, 0xffff0000, v25
	ds_read2st64_b32 v[18:19], v209 offset0:250 offset1:251
	ds_read2st64_b32 v[22:23], v209 offset0:252 offset1:253
	ds_read2st64_b32 v[24:25], v209 offset0:254 offset1:255
	s_waitcnt lgkmcnt(3)
	v_lshlrev_b32_e32 v222, 16, v16
	v_and_b32_e32 v223, 0xffff0000, v16
	s_waitcnt lgkmcnt(2)
	v_lshlrev_b32_e32 v34, 16, v18
	v_and_b32_e32 v35, 0xffff0000, v18
	v_lshlrev_b32_e32 v226, 16, v19
	v_and_b32_e32 v227, 0xffff0000, v19
	v_mov_b32_e32 v18, v88
	v_mov_b32_e32 v19, v90
	v_lshlrev_b32_e32 v224, 16, v17
	v_and_b32_e32 v225, 0xffff0000, v17
	s_waitcnt lgkmcnt(1)
	v_lshlrev_b32_e32 v17, 16, v23
	v_lshlrev_b32_e32 v16, 16, v22
	v_pk_mul_f32 v[18:19], v[18:19], v[20:21] op_sel_hi:[1,0]
	v_pk_fma_f32 v[76:77], v[178:179], v[64:65], v[38:39] neg_lo:[1,0,0] neg_hi:[1,0,0]
	v_pk_fma_f32 v[26:27], v[178:179], v[18:19], v[16:17] neg_lo:[1,0,0] neg_hi:[1,0,0]
	v_mov_b32_e32 v18, v89
	v_mov_b32_e32 v19, v91
	v_and_b32_e32 v17, 0xffff0000, v23
	v_and_b32_e32 v16, 0xffff0000, v22
	v_pk_mul_f32 v[18:19], v[18:19], v[20:21] op_sel_hi:[1,0]
	v_pk_mul_f32 v[38:39], v[128:129], v[20:21] op_sel_hi:[1,0]
	v_pk_fma_f32 v[28:29], v[178:179], v[18:19], v[16:17] neg_lo:[1,0,0] neg_hi:[1,0,0]
	v_mov_b32_e32 v18, v92
	v_pk_mul_f32 v[16:17], v[28:29], v[28:29]
	v_mov_b32_e32 v19, v94
	v_pk_fma_f32 v[32:33], v[26:27], v[26:27], v[16:17]
	s_waitcnt lgkmcnt(0)
	v_lshlrev_b32_e32 v17, 16, v25
	v_lshlrev_b32_e32 v16, 16, v24
	v_pk_mul_f32 v[18:19], v[18:19], v[20:21] op_sel_hi:[1,0]
	v_pk_fma_f32 v[148:149], v[178:179], v[38:39], v[36:37] neg_lo:[1,0,0] neg_hi:[1,0,0]
	v_pk_fma_f32 v[22:23], v[178:179], v[18:19], v[16:17] neg_lo:[1,0,0] neg_hi:[1,0,0]
	v_mov_b32_e32 v18, v93
	v_mov_b32_e32 v19, v95
	v_and_b32_e32 v17, 0xffff0000, v25
	v_and_b32_e32 v16, 0xffff0000, v24
	v_pk_mul_f32 v[18:19], v[18:19], v[20:21] op_sel_hi:[1,0]
	v_pk_mul_f32 v[36:37], v[134:135], v[20:21] op_sel_hi:[1,0]
	v_pk_fma_f32 v[24:25], v[178:179], v[18:19], v[16:17] neg_lo:[1,0,0] neg_hi:[1,0,0]
	v_pk_fma_f32 v[146:147], v[178:179], v[36:37], v[42:43] neg_lo:[1,0,0] neg_hi:[1,0,0]
	v_pk_mul_f32 v[36:37], v[132:133], v[20:21] op_sel_hi:[1,0]
	v_pk_mul_f32 v[16:17], v[24:25], v[24:25]
	v_pk_fma_f32 v[152:153], v[178:179], v[36:37], v[40:41] neg_lo:[1,0,0] neg_hi:[1,0,0]
	v_pk_mul_f32 v[36:37], v[138:139], v[20:21] op_sel_hi:[1,0]
	v_pk_fma_f32 v[150:151], v[22:23], v[22:23], v[16:17]
	global_load_dwordx4 v[16:19], v[186:187], off
	global_load_dwordx2 v[78:79], v[188:189], off
	v_pk_fma_f32 v[74:75], v[178:179], v[36:37], v[46:47] neg_lo:[1,0,0] neg_hi:[1,0,0]
	v_pk_mul_f32 v[36:37], v[136:137], v[20:21] op_sel_hi:[1,0]
	v_pk_mul_f32 v[228:229], v[76:77], v[76:77]
	v_pk_fma_f32 v[154:155], v[178:179], v[36:37], v[44:45] neg_lo:[1,0,0] neg_hi:[1,0,0]
	v_pk_mul_f32 v[36:37], v[142:143], v[20:21] op_sel_hi:[1,0]
	v_pk_mul_f32 v[230:231], v[148:149], v[148:149]
	v_pk_fma_f32 v[72:73], v[178:179], v[36:37], v[50:51] neg_lo:[1,0,0] neg_hi:[1,0,0]
	v_pk_mul_f32 v[36:37], v[140:141], v[20:21] op_sel_hi:[1,0]
	v_pk_mul_f32 v[234:235], v[152:153], v[152:153]
	v_pk_fma_f32 v[144:145], v[178:179], v[36:37], v[48:49] neg_lo:[1,0,0] neg_hi:[1,0,0]
	v_pk_mul_f32 v[36:37], v[114:115], v[20:21] op_sel_hi:[1,0]
	v_add_f32_e32 v173, v228, v229
	v_pk_fma_f32 v[68:69], v[178:179], v[36:37], v[54:55] neg_lo:[1,0,0] neg_hi:[1,0,0]
	v_pk_mul_f32 v[36:37], v[112:113], v[20:21] op_sel_hi:[1,0]
	v_pk_mul_f32 v[232:233], v[146:147], v[146:147]
	v_pk_fma_f32 v[70:71], v[178:179], v[36:37], v[52:53] neg_lo:[1,0,0] neg_hi:[1,0,0]
	v_pk_mul_f32 v[36:37], v[118:119], v[20:21] op_sel_hi:[1,0]
	v_pk_mul_f32 v[238:239], v[154:155], v[154:155]
	v_pk_fma_f32 v[64:65], v[178:179], v[36:37], v[58:59] neg_lo:[1,0,0] neg_hi:[1,0,0]
	v_pk_mul_f32 v[36:37], v[116:117], v[20:21] op_sel_hi:[1,0]
	v_pk_mul_f32 v[236:237], v[74:75], v[74:75]
	v_pk_fma_f32 v[66:67], v[178:179], v[36:37], v[56:57] neg_lo:[1,0,0] neg_hi:[1,0,0]
	v_pk_mul_f32 v[36:37], v[122:123], v[20:21] op_sel_hi:[1,0]
	v_pk_mul_f32 v[242:243], v[144:145], v[144:145]
	v_pk_fma_f32 v[60:61], v[178:179], v[36:37], v[60:61] neg_lo:[1,0,0] neg_hi:[1,0,0]
	v_pk_mul_f32 v[36:37], v[120:121], v[20:21] op_sel_hi:[1,0]
	v_pk_mul_f32 v[240:241], v[72:73], v[72:73]
	v_pk_fma_f32 v[62:63], v[178:179], v[36:37], v[62:63] neg_lo:[1,0,0] neg_hi:[1,0,0]
	v_pk_mul_f32 v[36:37], v[126:127], v[20:21] op_sel_hi:[1,0]
	v_pk_mul_f32 v[246:247], v[70:71], v[70:71]
	v_pk_fma_f32 v[56:57], v[178:179], v[36:37], v[158:159] neg_lo:[1,0,0] neg_hi:[1,0,0]
	v_pk_mul_f32 v[36:37], v[124:125], v[20:21] op_sel_hi:[1,0]
	v_pk_mul_f32 v[244:245], v[68:69], v[68:69]
	v_pk_fma_f32 v[58:59], v[178:179], v[36:37], v[156:157] neg_lo:[1,0,0] neg_hi:[1,0,0]
	v_pk_mul_f32 v[36:37], v[98:99], v[20:21] op_sel_hi:[1,0]
	v_pk_mul_f32 v[250:251], v[66:67], v[66:67]
	v_pk_fma_f32 v[52:53], v[178:179], v[36:37], v[162:163] neg_lo:[1,0,0] neg_hi:[1,0,0]
	v_pk_mul_f32 v[36:37], v[96:97], v[20:21] op_sel_hi:[1,0]
	v_pk_mul_f32 v[248:249], v[64:65], v[64:65]
	v_pk_fma_f32 v[54:55], v[178:179], v[36:37], v[160:161] neg_lo:[1,0,0] neg_hi:[1,0,0]
	v_pk_mul_f32 v[36:37], v[102:103], v[20:21] op_sel_hi:[1,0]
	v_pk_mul_f32 v[196:197], v[62:63], v[62:63]
	v_pk_fma_f32 v[48:49], v[178:179], v[36:37], v[166:167] neg_lo:[1,0,0] neg_hi:[1,0,0]
	v_pk_mul_f32 v[36:37], v[100:101], v[20:21] op_sel_hi:[1,0]
	v_pk_mul_f32 v[252:253], v[60:61], v[60:61]
	v_pk_fma_f32 v[50:51], v[178:179], v[36:37], v[164:165] neg_lo:[1,0,0] neg_hi:[1,0,0]
	v_pk_mul_f32 v[36:37], v[106:107], v[20:21] op_sel_hi:[1,0]
	v_pk_mul_f32 v[156:157], v[58:59], v[58:59]
	v_pk_fma_f32 v[44:45], v[178:179], v[36:37], v[170:171] neg_lo:[1,0,0] neg_hi:[1,0,0]
	v_pk_mul_f32 v[36:37], v[104:105], v[20:21] op_sel_hi:[1,0]
	v_pk_mul_f32 v[158:159], v[56:57], v[56:57]
	v_pk_fma_f32 v[46:47], v[178:179], v[36:37], v[168:169] neg_lo:[1,0,0] neg_hi:[1,0,0]
	v_pk_mul_f32 v[36:37], v[110:111], v[20:21] op_sel_hi:[1,0]
	v_add_f32_e32 v156, v156, v157
	v_pk_fma_f32 v[38:39], v[178:179], v[36:37], v[192:193] neg_lo:[1,0,0] neg_hi:[1,0,0]
	v_pk_mul_f32 v[36:37], v[108:109], v[20:21] op_sel_hi:[1,0]
	v_pk_mul_f32 v[160:161], v[54:55], v[54:55]
	v_pk_fma_f32 v[42:43], v[178:179], v[36:37], v[30:31] neg_lo:[1,0,0] neg_hi:[1,0,0]
	v_mov_b32_e32 v37, v39
	v_mov_b32_e32 v36, v43
	v_mov_b32_e32 v30, v42
	v_mov_b32_e32 v31, v38
	v_pk_mul_f32 v[36:37], v[36:37], v[36:37]
	v_pk_mul_f32 v[162:163], v[52:53], v[52:53]
	v_pk_fma_f32 v[192:193], v[30:31], v[30:31], v[36:37]
	v_pk_mul_f32 v[30:31], v[82:83], v[20:21] op_sel_hi:[1,0]
	v_pk_mul_f32 v[164:165], v[50:51], v[50:51]
	v_pk_fma_f32 v[36:37], v[178:179], v[30:31], v[224:225] neg_lo:[1,0,0] neg_hi:[1,0,0]
	v_pk_mul_f32 v[30:31], v[80:81], v[20:21] op_sel_hi:[1,0]
	v_pk_mul_f32 v[224:225], v[84:85], v[20:21] op_sel_hi:[1,0]
	v_pk_fma_f32 v[40:41], v[178:179], v[30:31], v[222:223] neg_lo:[1,0,0] neg_hi:[1,0,0]
	v_mov_b32_e32 v223, v37
	v_mov_b32_e32 v222, v41
	v_mov_b32_e32 v30, v40
	v_mov_b32_e32 v31, v36
	v_pk_mul_f32 v[222:223], v[222:223], v[222:223]
	v_pk_fma_f32 v[34:35], v[178:179], v[224:225], v[34:35] neg_lo:[1,0,0] neg_hi:[1,0,0]
	v_pk_fma_f32 v[222:223], v[30:31], v[30:31], v[222:223]
	v_pk_mul_f32 v[30:31], v[86:87], v[20:21] op_sel_hi:[1,0]
	v_mov_b32_e32 v224, v34
	v_pk_fma_f32 v[30:31], v[178:179], v[30:31], v[226:227] neg_lo:[1,0,0] neg_hi:[1,0,0]
	v_mov_b32_e32 v226, v35
	v_mov_b32_e32 v227, v31
	v_mov_b32_e32 v225, v30
	v_pk_mul_f32 v[226:227], v[226:227], v[226:227]
	v_add_f32_e32 v21, v234, v235
	v_pk_fma_f32 v[224:225], v[224:225], v[224:225], v[226:227]
	v_add_f32_e32 v226, v230, v231
	v_add_f32_e32 v173, v226, v173
	v_add_f32_e32 v21, v173, v21
	v_add_f32_e32 v173, v232, v233
	v_add_f32_e32 v21, v21, v173
	v_add_f32_e32 v173, v238, v239
	v_add_f32_e32 v21, v21, v173
	v_add_f32_e32 v173, v236, v237
	v_add_f32_e32 v21, v21, v173
	v_add_f32_e32 v173, v242, v243
	v_add_f32_e32 v21, v21, v173
	v_add_f32_e32 v173, v240, v241
	v_add_f32_e32 v21, v21, v173
	v_add_f32_e32 v173, v246, v247
	v_add_f32_e32 v21, v21, v173
	v_add_f32_e32 v173, v244, v245
	v_add_f32_e32 v21, v21, v173
	v_add_f32_e32 v173, v250, v251
	v_add_f32_e32 v21, v21, v173
	v_add_f32_e32 v173, v248, v249
	v_add_f32_e32 v21, v21, v173
	v_add_f32_e32 v173, v196, v197
	v_add_f32_e32 v21, v21, v173
	v_add_f32_e32 v173, v252, v253
	v_add_f32_e32 v21, v21, v173
	v_add_f32_e32 v21, v21, v156
	v_add_f32_e32 v156, v158, v159
	v_add_f32_e32 v21, v21, v156
	v_add_f32_e32 v156, v160, v161
	v_add_f32_e32 v21, v21, v156
	v_add_f32_e32 v156, v162, v163
	v_pk_mul_f32 v[166:167], v[48:49], v[48:49]
	v_add_f32_e32 v21, v21, v156
	v_add_f32_e32 v156, v164, v165
	v_pk_mul_f32 v[168:169], v[46:47], v[46:47]
	v_add_f32_e32 v21, v21, v156
	v_add_f32_e32 v156, v166, v167
	v_pk_mul_f32 v[170:171], v[44:45], v[44:45]
	v_add_f32_e32 v21, v21, v156
	v_add_f32_e32 v156, v168, v169
	v_add_f32_e32 v21, v21, v156
	v_add_f32_e32 v156, v170, v171
	v_add_f32_e32 v21, v21, v156
	v_add_f32_e32 v21, v21, v192
	v_add_f32_e32 v21, v21, v193
	v_add_f32_e32 v21, v21, v222
	v_add_f32_e32 v21, v21, v223
	v_add_f32_e32 v21, v21, v224
	v_add_f32_e32 v21, v21, v225
	v_add_f32_e32 v21, v21, v32
	v_add_f32_e32 v21, v21, v33
	v_add_f32_e32 v21, v21, v150
	v_add_f32_e32 v21, v21, v151
	ds_bpermute_b32 v32, v221, v21
	global_load_dwordx2 v[80:81], v[188:189], off offset:16
	global_load_dwordx4 v[112:115], v[186:187], off offset:32
	global_load_dwordx4 v[116:119], v[186:187], off offset:64
	global_load_dwordx2 v[82:83], v[188:189], off offset:32
	global_load_dwordx2 v[84:85], v[188:189], off offset:48
	global_load_dwordx4 v[120:123], v[186:187], off offset:96
	global_load_dwordx4 v[124:127], v[186:187], off offset:128
	global_load_dwordx2 v[86:87], v[188:189], off offset:64
	global_load_dwordx2 v[88:89], v[188:189], off offset:80
	global_load_dwordx4 v[128:131], v[186:187], off offset:160
	global_load_dwordx4 v[132:135], v[186:187], off offset:192
	global_load_dwordx2 v[90:91], v[188:189], off offset:96
	global_load_dwordx2 v[92:93], v[188:189], off offset:112
	global_load_dwordx4 v[136:139], v[186:187], off offset:224
	global_load_dwordx4 v[140:143], v[186:187], off offset:256
	global_load_dwordx2 v[94:95], v[188:189], off offset:128
	global_load_dwordx2 v[96:97], v[188:189], off offset:144
	global_load_dwordx4 v[158:161], v[186:187], off offset:288
	global_load_dwordx4 v[162:165], v[186:187], off offset:320
	global_load_dwordx2 v[98:99], v[188:189], off offset:160
	global_load_dwordx2 v[100:101], v[188:189], off offset:176
	global_load_dwordx4 v[166:169], v[186:187], off offset:352
	global_load_dwordx4 v[108:111], v[186:187], off offset:384
	global_load_dwordx2 v[102:103], v[188:189], off offset:192
	global_load_dwordx2 v[104:105], v[188:189], off offset:208
	global_load_dwordx2 v[106:107], v[188:189], off offset:224
	global_load_dwordx2 v[170:171], v[188:189], off offset:240
	s_waitcnt vmcnt(27)
	v_lshlrev_b32_e32 v156, 16, v78
	v_and_b32_e32 v157, 0xffff0000, v78
	v_lshlrev_b32_e32 v78, 16, v79
	v_and_b32_e32 v79, 0xffff0000, v79
	s_waitcnt lgkmcnt(0)
	v_add_f32_e32 v21, v21, v32
	v_fmamk_f32 v21, v21, 0x3c000000, v195
	v_mul_f32_e32 v32, 0x4b800000, v21
	v_cmp_gt_f32_e32 vcc, s15, v21
	s_nop 0
	v_cndmask_b32_e32 v21, v21, v32, vcc
	v_rsq_f32_e32 v21, v21
	s_nop 0
	v_mul_f32_e32 v32, 0x45800000, v21
	v_cndmask_b32_e32 v21, v21, v32, vcc
	v_mul_f32_e32 v32, v207, v21
	v_pk_mul_f32 v[148:149], v[148:149], v[32:33] op_sel_hi:[1,0]
	v_pk_mul_f32 v[76:77], v[76:77], v[32:33] op_sel_hi:[1,0]
	v_pk_mul_f32 v[16:17], v[16:17], v[148:149]
	v_pk_mul_f32 v[18:19], v[18:19], v[76:77]
	v_pk_mul_f32 v[16:17], v[16:17], v[156:157]
	v_pk_mul_f32 v[18:19], v[18:19], v[78:79]
	v_cvt_pk_bf16_f32 v16, v16, v17
	v_cvt_pk_bf16_f32 v17, v18, v19
	global_store_dwordx2 v[190:191], v[16:17], off
	v_pk_mul_f32 v[148:149], v[152:153], v[32:33] op_sel_hi:[1,0]
	v_pk_mul_f32 v[74:75], v[74:75], v[32:33] op_sel_hi:[1,0]
	v_pk_mul_f32 v[72:73], v[72:73], v[32:33] op_sel_hi:[1,0]
	v_pk_mul_f32 v[70:71], v[70:71], v[32:33] op_sel_hi:[1,0]
	v_pk_mul_f32 v[68:69], v[68:69], v[32:33] op_sel_hi:[1,0]
	v_pk_mul_f32 v[66:67], v[66:67], v[32:33] op_sel_hi:[1,0]
	v_pk_mul_f32 v[64:65], v[64:65], v[32:33] op_sel_hi:[1,0]
	v_pk_mul_f32 v[62:63], v[62:63], v[32:33] op_sel_hi:[1,0]
	v_pk_mul_f32 v[60:61], v[60:61], v[32:33] op_sel_hi:[1,0]
	v_pk_mul_f32 v[58:59], v[58:59], v[32:33] op_sel_hi:[1,0]
	v_pk_mul_f32 v[56:57], v[56:57], v[32:33] op_sel_hi:[1,0]
	v_pk_mul_f32 v[54:55], v[54:55], v[32:33] op_sel_hi:[1,0]
	v_pk_mul_f32 v[52:53], v[52:53], v[32:33] op_sel_hi:[1,0]
	v_pk_mul_f32 v[50:51], v[50:51], v[32:33] op_sel_hi:[1,0]
	v_pk_mul_f32 v[48:49], v[48:49], v[32:33] op_sel_hi:[1,0]
	v_pk_mul_f32 v[46:47], v[46:47], v[32:33] op_sel_hi:[1,0]
	v_pk_mul_f32 v[44:45], v[44:45], v[32:33] op_sel_hi:[1,0]
	v_pk_mul_f32 v[42:43], v[42:43], v[32:33] op_sel_hi:[1,0]
	v_pk_mul_f32 v[38:39], v[38:39], v[32:33] op_sel_hi:[1,0]
	v_pk_mul_f32 v[40:41], v[40:41], v[32:33] op_sel_hi:[1,0]
	v_pk_mul_f32 v[36:37], v[36:37], v[32:33] op_sel_hi:[1,0]
	v_pk_mul_f32 v[34:35], v[34:35], v[32:33] op_sel_hi:[1,0]
	v_pk_mul_f32 v[30:31], v[30:31], v[32:33] op_sel_hi:[1,0]
	s_waitcnt vmcnt(27)
	v_lshlrev_b32_e32 v76, 16, v80
	v_and_b32_e32 v77, 0xffff0000, v80
	v_lshlrev_b32_e32 v78, 16, v81
	v_and_b32_e32 v79, 0xffff0000, v81
	s_waitcnt vmcnt(26)
	v_pk_mul_f32 v[16:17], v[112:113], v[148:149]
	s_nop 0
	v_pk_mul_f32 v[16:17], v[16:17], v[76:77]
	v_pk_mul_f32 v[76:77], v[146:147], v[32:33] op_sel_hi:[1,0]
	v_cvt_pk_bf16_f32 v16, v16, v17
	v_pk_mul_f32 v[18:19], v[114:115], v[76:77]
	s_nop 0
	v_pk_mul_f32 v[18:19], v[18:19], v[78:79]
	v_pk_mul_f32 v[78:79], v[154:155], v[32:33] op_sel_hi:[1,0]
	v_cvt_pk_bf16_f32 v17, v18, v19
	global_store_dwordx2 v[190:191], v[16:17], off offset:16
	s_waitcnt vmcnt(26)
	v_pk_mul_f32 v[16:17], v[116:117], v[78:79]
	s_waitcnt vmcnt(25)
	v_lshlrev_b32_e32 v146, 16, v82
	v_and_b32_e32 v147, 0xffff0000, v82
	v_pk_mul_f32 v[18:19], v[118:119], v[74:75]
	v_lshlrev_b32_e32 v74, 16, v83
	v_and_b32_e32 v75, 0xffff0000, v83
	v_pk_mul_f32 v[16:17], v[16:17], v[146:147]
	v_pk_mul_f32 v[18:19], v[18:19], v[74:75]
	v_cvt_pk_bf16_f32 v16, v16, v17
	v_cvt_pk_bf16_f32 v17, v18, v19
	global_store_dwordx2 v[190:191], v[16:17], off offset:32
	v_pk_mul_f32 v[74:75], v[144:145], v[32:33] op_sel_hi:[1,0]
	s_waitcnt vmcnt(25)
	v_lshlrev_b32_e32 v76, 16, v84
	v_and_b32_e32 v77, 0xffff0000, v84
	v_lshlrev_b32_e32 v78, 16, v85
	v_and_b32_e32 v79, 0xffff0000, v85
	s_waitcnt vmcnt(24)
	v_pk_mul_f32 v[16:17], v[120:121], v[74:75]
	v_pk_mul_f32 v[18:19], v[122:123], v[72:73]
	v_pk_mul_f32 v[16:17], v[16:17], v[76:77]
	v_pk_mul_f32 v[18:19], v[18:19], v[78:79]
	v_cvt_pk_bf16_f32 v16, v16, v17
	v_cvt_pk_bf16_f32 v17, v18, v19
	global_store_dwordx2 v[190:191], v[16:17], off offset:48
	s_waitcnt vmcnt(24)
	v_pk_mul_f32 v[16:17], v[70:71], v[124:125]
	s_waitcnt vmcnt(23)
	v_lshlrev_b32_e32 v70, 16, v86
	v_and_b32_e32 v71, 0xffff0000, v86
	v_pk_mul_f32 v[18:19], v[68:69], v[126:127]
	v_lshlrev_b32_e32 v68, 16, v87
	v_and_b32_e32 v69, 0xffff0000, v87
	v_pk_mul_f32 v[16:17], v[16:17], v[70:71]
	v_pk_mul_f32 v[18:19], v[18:19], v[68:69]
	v_cvt_pk_bf16_f32 v16, v16, v17
	v_cvt_pk_bf16_f32 v17, v18, v19
	global_store_dwordx2 v[190:191], v[16:17], off offset:64
	s_waitcnt vmcnt(23)
	v_lshlrev_b32_e32 v68, 16, v88
	v_and_b32_e32 v69, 0xffff0000, v88
	v_lshlrev_b32_e32 v70, 16, v89
	v_and_b32_e32 v71, 0xffff0000, v89
	s_waitcnt vmcnt(22)
	v_pk_mul_f32 v[16:17], v[66:67], v[128:129]
	v_pk_mul_f32 v[18:19], v[64:65], v[130:131]
	v_pk_mul_f32 v[16:17], v[16:17], v[68:69]
	v_pk_mul_f32 v[18:19], v[18:19], v[70:71]
	v_cvt_pk_bf16_f32 v16, v16, v17
	v_cvt_pk_bf16_f32 v17, v18, v19
	global_store_dwordx2 v[190:191], v[16:17], off offset:80
	s_waitcnt vmcnt(22)
	v_pk_mul_f32 v[16:17], v[62:63], v[132:133]
	s_waitcnt vmcnt(21)
	v_lshlrev_b32_e32 v62, 16, v90
	v_and_b32_e32 v63, 0xffff0000, v90
	v_pk_mul_f32 v[18:19], v[60:61], v[134:135]
	v_lshlrev_b32_e32 v60, 16, v91
	v_and_b32_e32 v61, 0xffff0000, v91
	v_pk_mul_f32 v[16:17], v[16:17], v[62:63]
	v_pk_mul_f32 v[18:19], v[18:19], v[60:61]
	v_cvt_pk_bf16_f32 v16, v16, v17
	v_cvt_pk_bf16_f32 v17, v18, v19
	global_store_dwordx2 v[190:191], v[16:17], off offset:96
	s_waitcnt vmcnt(21)
	v_lshlrev_b32_e32 v60, 16, v92
	v_and_b32_e32 v61, 0xffff0000, v92
	v_lshlrev_b32_e32 v62, 16, v93
	v_and_b32_e32 v63, 0xffff0000, v93
	s_waitcnt vmcnt(20)
	v_pk_mul_f32 v[16:17], v[58:59], v[136:137]
	v_pk_mul_f32 v[18:19], v[56:57], v[138:139]
	v_pk_mul_f32 v[16:17], v[16:17], v[60:61]
	v_pk_mul_f32 v[18:19], v[18:19], v[62:63]
	v_cvt_pk_bf16_f32 v16, v16, v17
	v_cvt_pk_bf16_f32 v17, v18, v19
	global_store_dwordx2 v[190:191], v[16:17], off offset:112
	s_waitcnt vmcnt(20)
	v_pk_mul_f32 v[16:17], v[54:55], v[140:141]
	s_waitcnt vmcnt(19)
	v_lshlrev_b32_e32 v54, 16, v94
	v_and_b32_e32 v55, 0xffff0000, v94
	v_pk_mul_f32 v[18:19], v[52:53], v[142:143]
	v_lshlrev_b32_e32 v52, 16, v95
	v_and_b32_e32 v53, 0xffff0000, v95
	v_pk_mul_f32 v[16:17], v[16:17], v[54:55]
	v_pk_mul_f32 v[18:19], v[18:19], v[52:53]
	v_cvt_pk_bf16_f32 v16, v16, v17
	v_cvt_pk_bf16_f32 v17, v18, v19
	global_store_dwordx2 v[190:191], v[16:17], off offset:128
	s_waitcnt vmcnt(19)
	v_lshlrev_b32_e32 v52, 16, v96
	v_and_b32_e32 v53, 0xffff0000, v96
	v_lshlrev_b32_e32 v54, 16, v97
	v_and_b32_e32 v55, 0xffff0000, v97
	s_waitcnt vmcnt(18)
	v_pk_mul_f32 v[16:17], v[50:51], v[158:159]
	v_pk_mul_f32 v[18:19], v[48:49], v[160:161]
	v_pk_mul_f32 v[16:17], v[16:17], v[52:53]
	v_pk_mul_f32 v[18:19], v[18:19], v[54:55]
	v_cvt_pk_bf16_f32 v16, v16, v17
	v_cvt_pk_bf16_f32 v17, v18, v19
	global_store_dwordx2 v[190:191], v[16:17], off offset:144
	s_waitcnt vmcnt(18)
	v_pk_mul_f32 v[16:17], v[46:47], v[162:163]
	s_waitcnt vmcnt(17)
	v_lshlrev_b32_e32 v46, 16, v98
	v_and_b32_e32 v47, 0xffff0000, v98
	v_pk_mul_f32 v[18:19], v[44:45], v[164:165]
	v_lshlrev_b32_e32 v44, 16, v99
	v_and_b32_e32 v45, 0xffff0000, v99
	v_pk_mul_f32 v[16:17], v[16:17], v[46:47]
	v_pk_mul_f32 v[18:19], v[18:19], v[44:45]
	v_cvt_pk_bf16_f32 v16, v16, v17
	v_cvt_pk_bf16_f32 v17, v18, v19
	global_store_dwordx2 v[190:191], v[16:17], off offset:160
	s_waitcnt vmcnt(17)
	v_lshlrev_b32_e32 v44, 16, v100
	v_and_b32_e32 v45, 0xffff0000, v100
	v_lshlrev_b32_e32 v46, 16, v101
	v_and_b32_e32 v47, 0xffff0000, v101
	s_waitcnt vmcnt(16)
	v_pk_mul_f32 v[16:17], v[42:43], v[166:167]
	v_pk_mul_f32 v[18:19], v[38:39], v[168:169]
	v_pk_mul_f32 v[16:17], v[16:17], v[44:45]
	v_pk_mul_f32 v[18:19], v[18:19], v[46:47]
	v_cvt_pk_bf16_f32 v16, v16, v17
	v_cvt_pk_bf16_f32 v17, v18, v19
	global_store_dwordx2 v[190:191], v[16:17], off offset:176
	s_waitcnt vmcnt(16)
	v_pk_mul_f32 v[16:17], v[40:41], v[108:109]
	s_waitcnt vmcnt(15)
	v_lshlrev_b32_e32 v40, 16, v102
	v_and_b32_e32 v41, 0xffff0000, v102
	v_pk_mul_f32 v[18:19], v[36:37], v[110:111]
	v_lshlrev_b32_e32 v36, 16, v103
	v_and_b32_e32 v37, 0xffff0000, v103
	v_pk_mul_f32 v[16:17], v[16:17], v[40:41]
	v_pk_mul_f32 v[18:19], v[18:19], v[36:37]
	v_cvt_pk_bf16_f32 v16, v16, v17
	v_cvt_pk_bf16_f32 v17, v18, v19
	global_store_dwordx2 v[190:191], v[16:17], off offset:192
	global_load_dwordx4 v[16:19], v[186:187], off offset:416
	s_waitcnt vmcnt(16)
	v_lshlrev_b32_e32 v36, 16, v104
	v_and_b32_e32 v37, 0xffff0000, v104
	v_lshlrev_b32_e32 v38, 16, v105
	v_and_b32_e32 v39, 0xffff0000, v105
	s_waitcnt vmcnt(0)
	v_pk_mul_f32 v[16:17], v[34:35], v[16:17]
	v_pk_mul_f32 v[18:19], v[30:31], v[18:19]
	v_pk_mul_f32 v[16:17], v[16:17], v[36:37]
	v_pk_mul_f32 v[18:19], v[18:19], v[38:39]
	v_cvt_pk_bf16_f32 v16, v16, v17
	v_cvt_pk_bf16_f32 v17, v18, v19
	global_store_dwordx2 v[190:191], v[16:17], off offset:208
	global_load_dwordx4 v[16:19], v[186:187], off offset:448
	v_mov_b32_e32 v34, v26
	v_mov_b32_e32 v35, v28
	v_mov_b32_e32 v28, v27
	v_pk_mul_f32 v[26:27], v[34:35], v[32:33] op_sel_hi:[1,0]
	v_pk_mul_f32 v[28:29], v[28:29], v[32:33] op_sel_hi:[1,0]
	s_waitcnt vmcnt(0)
	v_pk_mul_f32 v[16:17], v[26:27], v[16:17]
	v_lshlrev_b32_e32 v26, 16, v106
	v_and_b32_e32 v27, 0xffff0000, v106
	v_pk_mul_f32 v[18:19], v[28:29], v[18:19]
	v_lshlrev_b32_e32 v28, 16, v107
	v_and_b32_e32 v29, 0xffff0000, v107
	v_pk_mul_f32 v[16:17], v[16:17], v[26:27]
	v_pk_mul_f32 v[18:19], v[18:19], v[28:29]
	v_cvt_pk_bf16_f32 v16, v16, v17
	v_cvt_pk_bf16_f32 v17, v18, v19
	global_store_dwordx2 v[190:191], v[16:17], off offset:224
	global_load_dwordx4 v[16:19], v[186:187], off offset:480
	v_mov_b32_e32 v26, v22
	v_mov_b32_e32 v27, v24
	v_mov_b32_e32 v24, v23
	v_pk_mul_f32 v[22:23], v[26:27], v[32:33] op_sel_hi:[1,0]
	v_pk_mul_f32 v[24:25], v[24:25], v[32:33] op_sel_hi:[1,0]
	v_lshlrev_b32_e32 v26, 16, v170
	v_and_b32_e32 v27, 0xffff0000, v170
	v_lshlrev_b32_e32 v28, 16, v171
	v_and_b32_e32 v29, 0xffff0000, v171
	s_waitcnt vmcnt(0)
	v_pk_mul_f32 v[16:17], v[22:23], v[16:17]
	v_pk_mul_f32 v[18:19], v[24:25], v[18:19]
	v_pk_mul_f32 v[16:17], v[16:17], v[26:27]
	v_pk_mul_f32 v[18:19], v[18:19], v[28:29]
	v_cvt_pk_bf16_f32 v16, v16, v17
	v_cvt_pk_bf16_f32 v17, v18, v19
	global_store_dwordx2 v[190:191], v[16:17], off offset:240
	s_cbranch_execnz .LBB0_498
	s_branch .LBB0_530

.LBB0_562:
	ds_bpermute_b32 v16, v221, v193
	s_waitcnt lgkmcnt(0)
	s_barrier
	s_waitcnt lgkmcnt(0)
	v_add_f32_e32 v16, v193, v16
	v_div_scale_f32 v17, s[16:17], v16, v16, 1.0
	v_rcp_f32_e32 v18, v17
	v_div_scale_f32 v19, vcc, 1.0, v16, 1.0
	v_fma_f32 v20, -v17, v18, 1.0
	v_fmac_f32_e32 v18, v20, v18
	v_mul_f32_e32 v20, v19, v18
	v_fma_f32 v21, -v17, v20, v19
	v_fmac_f32_e32 v20, v21, v18
	v_fma_f32 v17, -v17, v20, v19
	v_div_fmas_f32 v17, v17, v18, v20
	v_div_fixup_f32 v20, v17, v16, 1.0
	v_cndmask_b32_e64 v16, 0, 1, s[6:7]
	v_cmp_ne_u32_e64 s[72:73], 1, v16
	s_andn2_b64 vcc, exec, s[6:7]
	s_mov_b64 s[6:7], -1
	s_cbranch_vccnz .LBB0_564
	ds_read2st64_b32 v[16:17], v209 offset0:224 offset1:225
	ds_read2st64_b32 v[18:19], v209 offset0:226 offset1:227
	ds_read2st64_b32 v[22:23], v209 offset0:228 offset1:229
	ds_read2st64_b32 v[24:25], v209 offset0:230 offset1:231
	v_pk_mul_f32 v[64:65], v[130:131], v[20:21] op_sel_hi:[1,0]
	s_waitcnt lgkmcnt(3)
	v_lshlrev_b32_e32 v36, 16, v16
	v_and_b32_e32 v37, 0xffff0000, v16
	v_lshlrev_b32_e32 v38, 16, v17
	v_and_b32_e32 v39, 0xffff0000, v17
	ds_read2st64_b32 v[16:17], v209 offset0:232 offset1:233
	s_waitcnt lgkmcnt(3)
	v_lshlrev_b32_e32 v40, 16, v18
	v_and_b32_e32 v41, 0xffff0000, v18
	v_lshlrev_b32_e32 v42, 16, v19
	v_and_b32_e32 v43, 0xffff0000, v19
	s_waitcnt lgkmcnt(2)
	v_lshlrev_b32_e32 v44, 16, v22
	v_and_b32_e32 v45, 0xffff0000, v22
	v_lshlrev_b32_e32 v46, 16, v23
	v_and_b32_e32 v47, 0xffff0000, v23
	s_waitcnt lgkmcnt(1)
	v_lshlrev_b32_e32 v48, 16, v24
	v_and_b32_e32 v49, 0xffff0000, v24
	v_lshlrev_b32_e32 v50, 16, v25
	v_and_b32_e32 v51, 0xffff0000, v25
	ds_read2st64_b32 v[18:19], v209 offset0:234 offset1:235
	ds_read2st64_b32 v[22:23], v209 offset0:236 offset1:237
	ds_read2st64_b32 v[24:25], v209 offset0:238 offset1:239
	s_waitcnt lgkmcnt(3)
	v_lshlrev_b32_e32 v52, 16, v16
	v_and_b32_e32 v53, 0xffff0000, v16
	v_lshlrev_b32_e32 v54, 16, v17
	v_and_b32_e32 v55, 0xffff0000, v17
	ds_read2st64_b32 v[16:17], v209 offset0:240 offset1:241
	s_waitcnt lgkmcnt(3)
	v_lshlrev_b32_e32 v56, 16, v18
	v_and_b32_e32 v57, 0xffff0000, v18
	v_lshlrev_b32_e32 v58, 16, v19
	v_and_b32_e32 v59, 0xffff0000, v19
	s_waitcnt lgkmcnt(2)
	v_lshlrev_b32_e32 v62, 16, v22
	v_and_b32_e32 v63, 0xffff0000, v22
	v_lshlrev_b32_e32 v60, 16, v23
	v_and_b32_e32 v61, 0xffff0000, v23
	s_waitcnt lgkmcnt(1)
	v_lshlrev_b32_e32 v156, 16, v24
	v_and_b32_e32 v157, 0xffff0000, v24
	v_lshlrev_b32_e32 v158, 16, v25
	v_and_b32_e32 v159, 0xffff0000, v25
	ds_read2st64_b32 v[18:19], v209 offset0:242 offset1:243
	ds_read2st64_b32 v[22:23], v209 offset0:244 offset1:245
	ds_read2st64_b32 v[24:25], v209 offset0:246 offset1:247
	s_waitcnt lgkmcnt(3)
	v_lshlrev_b32_e32 v160, 16, v16
	v_and_b32_e32 v161, 0xffff0000, v16
	v_lshlrev_b32_e32 v162, 16, v17
	v_and_b32_e32 v163, 0xffff0000, v17
	ds_read2st64_b32 v[16:17], v209 offset0:248 offset1:249
	s_waitcnt lgkmcnt(3)
	v_lshlrev_b32_e32 v164, 16, v18
	v_and_b32_e32 v165, 0xffff0000, v18
	v_lshlrev_b32_e32 v166, 16, v19
	v_and_b32_e32 v167, 0xffff0000, v19
	s_waitcnt lgkmcnt(2)
	v_lshlrev_b32_e32 v168, 16, v22
	v_and_b32_e32 v169, 0xffff0000, v22
	v_lshlrev_b32_e32 v170, 16, v23
	v_and_b32_e32 v171, 0xffff0000, v23
	s_waitcnt lgkmcnt(1)
	v_lshlrev_b32_e32 v30, 16, v24
	v_and_b32_e32 v31, 0xffff0000, v24
	v_lshlrev_b32_e32 v192, 16, v25
	v_and_b32_e32 v193, 0xffff0000, v25
	ds_read2st64_b32 v[18:19], v209 offset0:250 offset1:251
	ds_read2st64_b32 v[22:23], v209 offset0:252 offset1:253
	ds_read2st64_b32 v[24:25], v209 offset0:254 offset1:255
	s_waitcnt lgkmcnt(3)
	v_lshlrev_b32_e32 v196, 16, v16
	v_and_b32_e32 v197, 0xffff0000, v16
	s_waitcnt lgkmcnt(2)
	v_lshlrev_b32_e32 v34, 16, v18
	v_and_b32_e32 v35, 0xffff0000, v18
	v_lshlrev_b32_e32 v224, 16, v19
	v_and_b32_e32 v225, 0xffff0000, v19
	v_mov_b32_e32 v18, v88
	v_mov_b32_e32 v19, v90
	v_lshlrev_b32_e32 v222, 16, v17
	v_and_b32_e32 v223, 0xffff0000, v17
	s_waitcnt lgkmcnt(1)
	v_lshlrev_b32_e32 v17, 16, v23
	v_lshlrev_b32_e32 v16, 16, v22
	v_pk_mul_f32 v[18:19], v[18:19], v[20:21] op_sel_hi:[1,0]
	v_pk_fma_f32 v[76:77], v[178:179], v[64:65], v[38:39] neg_lo:[1,0,0] neg_hi:[1,0,0]
	v_pk_fma_f32 v[26:27], v[178:179], v[18:19], v[16:17] neg_lo:[1,0,0] neg_hi:[1,0,0]
	v_mov_b32_e32 v18, v89
	v_mov_b32_e32 v19, v91
	v_and_b32_e32 v17, 0xffff0000, v23
	v_and_b32_e32 v16, 0xffff0000, v22
	v_pk_mul_f32 v[18:19], v[18:19], v[20:21] op_sel_hi:[1,0]
	v_pk_mul_f32 v[38:39], v[128:129], v[20:21] op_sel_hi:[1,0]
	v_pk_fma_f32 v[28:29], v[178:179], v[18:19], v[16:17] neg_lo:[1,0,0] neg_hi:[1,0,0]
	v_mov_b32_e32 v18, v92
	v_pk_mul_f32 v[16:17], v[28:29], v[28:29]
	v_mov_b32_e32 v19, v94
	v_pk_fma_f32 v[32:33], v[26:27], v[26:27], v[16:17]
	s_waitcnt lgkmcnt(0)
	v_lshlrev_b32_e32 v17, 16, v25
	v_lshlrev_b32_e32 v16, 16, v24
	v_pk_mul_f32 v[18:19], v[18:19], v[20:21] op_sel_hi:[1,0]
	v_pk_fma_f32 v[148:149], v[178:179], v[38:39], v[36:37] neg_lo:[1,0,0] neg_hi:[1,0,0]
	v_pk_fma_f32 v[22:23], v[178:179], v[18:19], v[16:17] neg_lo:[1,0,0] neg_hi:[1,0,0]
	v_mov_b32_e32 v18, v93
	v_mov_b32_e32 v19, v95
	v_and_b32_e32 v17, 0xffff0000, v25
	v_and_b32_e32 v16, 0xffff0000, v24
	v_pk_mul_f32 v[18:19], v[18:19], v[20:21] op_sel_hi:[1,0]
	v_pk_mul_f32 v[36:37], v[134:135], v[20:21] op_sel_hi:[1,0]
	v_pk_fma_f32 v[24:25], v[178:179], v[18:19], v[16:17] neg_lo:[1,0,0] neg_hi:[1,0,0]
	v_pk_fma_f32 v[146:147], v[178:179], v[36:37], v[42:43] neg_lo:[1,0,0] neg_hi:[1,0,0]
	v_pk_mul_f32 v[36:37], v[132:133], v[20:21] op_sel_hi:[1,0]
	v_pk_mul_f32 v[16:17], v[24:25], v[24:25]
	v_pk_fma_f32 v[152:153], v[178:179], v[36:37], v[40:41] neg_lo:[1,0,0] neg_hi:[1,0,0]
	v_pk_mul_f32 v[36:37], v[138:139], v[20:21] op_sel_hi:[1,0]
	v_pk_fma_f32 v[150:151], v[22:23], v[22:23], v[16:17]
	global_load_dwordx4 v[16:19], v[186:187], off
	global_load_dwordx2 v[78:79], v[188:189], off
	v_pk_fma_f32 v[74:75], v[178:179], v[36:37], v[46:47] neg_lo:[1,0,0] neg_hi:[1,0,0]
	v_pk_mul_f32 v[36:37], v[136:137], v[20:21] op_sel_hi:[1,0]
	v_pk_mul_f32 v[226:227], v[76:77], v[76:77]
	v_pk_fma_f32 v[154:155], v[178:179], v[36:37], v[44:45] neg_lo:[1,0,0] neg_hi:[1,0,0]
	v_pk_mul_f32 v[36:37], v[142:143], v[20:21] op_sel_hi:[1,0]
	v_pk_mul_f32 v[228:229], v[148:149], v[148:149]
	v_pk_fma_f32 v[72:73], v[178:179], v[36:37], v[50:51] neg_lo:[1,0,0] neg_hi:[1,0,0]
	v_pk_mul_f32 v[36:37], v[140:141], v[20:21] op_sel_hi:[1,0]
	v_pk_mul_f32 v[232:233], v[152:153], v[152:153]
	v_pk_fma_f32 v[144:145], v[178:179], v[36:37], v[48:49] neg_lo:[1,0,0] neg_hi:[1,0,0]
	v_pk_mul_f32 v[36:37], v[114:115], v[20:21] op_sel_hi:[1,0]
	v_add_f32_e32 v173, v226, v227
	v_pk_fma_f32 v[68:69], v[178:179], v[36:37], v[54:55] neg_lo:[1,0,0] neg_hi:[1,0,0]
	v_pk_mul_f32 v[36:37], v[112:113], v[20:21] op_sel_hi:[1,0]
	v_pk_mul_f32 v[230:231], v[146:147], v[146:147]
	v_pk_fma_f32 v[70:71], v[178:179], v[36:37], v[52:53] neg_lo:[1,0,0] neg_hi:[1,0,0]
	v_pk_mul_f32 v[36:37], v[118:119], v[20:21] op_sel_hi:[1,0]
	v_pk_mul_f32 v[236:237], v[154:155], v[154:155]
	v_pk_fma_f32 v[64:65], v[178:179], v[36:37], v[58:59] neg_lo:[1,0,0] neg_hi:[1,0,0]
	v_pk_mul_f32 v[36:37], v[116:117], v[20:21] op_sel_hi:[1,0]
	v_pk_mul_f32 v[234:235], v[74:75], v[74:75]
	v_pk_fma_f32 v[66:67], v[178:179], v[36:37], v[56:57] neg_lo:[1,0,0] neg_hi:[1,0,0]
	v_pk_mul_f32 v[36:37], v[122:123], v[20:21] op_sel_hi:[1,0]
	v_pk_mul_f32 v[240:241], v[144:145], v[144:145]
	v_pk_fma_f32 v[60:61], v[178:179], v[36:37], v[60:61] neg_lo:[1,0,0] neg_hi:[1,0,0]
	v_pk_mul_f32 v[36:37], v[120:121], v[20:21] op_sel_hi:[1,0]
	v_pk_mul_f32 v[238:239], v[72:73], v[72:73]
	v_pk_fma_f32 v[62:63], v[178:179], v[36:37], v[62:63] neg_lo:[1,0,0] neg_hi:[1,0,0]
	v_pk_mul_f32 v[36:37], v[126:127], v[20:21] op_sel_hi:[1,0]
	v_pk_mul_f32 v[244:245], v[70:71], v[70:71]
	v_pk_fma_f32 v[56:57], v[178:179], v[36:37], v[158:159] neg_lo:[1,0,0] neg_hi:[1,0,0]
	v_pk_mul_f32 v[36:37], v[124:125], v[20:21] op_sel_hi:[1,0]
	v_pk_mul_f32 v[242:243], v[68:69], v[68:69]
	v_pk_fma_f32 v[58:59], v[178:179], v[36:37], v[156:157] neg_lo:[1,0,0] neg_hi:[1,0,0]
	v_pk_mul_f32 v[36:37], v[98:99], v[20:21] op_sel_hi:[1,0]
	v_pk_mul_f32 v[248:249], v[66:67], v[66:67]
	v_pk_fma_f32 v[52:53], v[178:179], v[36:37], v[162:163] neg_lo:[1,0,0] neg_hi:[1,0,0]
	v_pk_mul_f32 v[36:37], v[96:97], v[20:21] op_sel_hi:[1,0]
	v_pk_mul_f32 v[246:247], v[64:65], v[64:65]
	v_pk_fma_f32 v[54:55], v[178:179], v[36:37], v[160:161] neg_lo:[1,0,0] neg_hi:[1,0,0]
	v_pk_mul_f32 v[36:37], v[102:103], v[20:21] op_sel_hi:[1,0]
	v_pk_mul_f32 v[252:253], v[62:63], v[62:63]
	v_pk_fma_f32 v[48:49], v[178:179], v[36:37], v[166:167] neg_lo:[1,0,0] neg_hi:[1,0,0]
	v_pk_mul_f32 v[36:37], v[100:101], v[20:21] op_sel_hi:[1,0]
	v_pk_mul_f32 v[250:251], v[60:61], v[60:61]
	v_pk_fma_f32 v[50:51], v[178:179], v[36:37], v[164:165] neg_lo:[1,0,0] neg_hi:[1,0,0]
	v_pk_mul_f32 v[36:37], v[106:107], v[20:21] op_sel_hi:[1,0]
	v_pk_mul_f32 v[156:157], v[58:59], v[58:59]
	v_pk_fma_f32 v[44:45], v[178:179], v[36:37], v[170:171] neg_lo:[1,0,0] neg_hi:[1,0,0]
	v_pk_mul_f32 v[36:37], v[104:105], v[20:21] op_sel_hi:[1,0]
	v_pk_mul_f32 v[158:159], v[56:57], v[56:57]
	v_pk_fma_f32 v[46:47], v[178:179], v[36:37], v[168:169] neg_lo:[1,0,0] neg_hi:[1,0,0]
	v_pk_mul_f32 v[36:37], v[110:111], v[20:21] op_sel_hi:[1,0]
	v_add_f32_e32 v156, v156, v157
	v_pk_fma_f32 v[38:39], v[178:179], v[36:37], v[192:193] neg_lo:[1,0,0] neg_hi:[1,0,0]
	v_pk_mul_f32 v[36:37], v[108:109], v[20:21] op_sel_hi:[1,0]
	v_pk_mul_f32 v[160:161], v[54:55], v[54:55]
	v_pk_fma_f32 v[42:43], v[178:179], v[36:37], v[30:31] neg_lo:[1,0,0] neg_hi:[1,0,0]
	v_mov_b32_e32 v37, v39
	v_mov_b32_e32 v36, v43
	v_mov_b32_e32 v30, v42
	v_mov_b32_e32 v31, v38
	v_pk_mul_f32 v[36:37], v[36:37], v[36:37]
	v_pk_mul_f32 v[162:163], v[52:53], v[52:53]
	v_pk_fma_f32 v[192:193], v[30:31], v[30:31], v[36:37]
	v_pk_mul_f32 v[30:31], v[82:83], v[20:21] op_sel_hi:[1,0]
	v_pk_mul_f32 v[164:165], v[50:51], v[50:51]
	v_pk_fma_f32 v[36:37], v[178:179], v[30:31], v[222:223] neg_lo:[1,0,0] neg_hi:[1,0,0]
	v_pk_mul_f32 v[30:31], v[80:81], v[20:21] op_sel_hi:[1,0]
	v_pk_mul_f32 v[222:223], v[84:85], v[20:21] op_sel_hi:[1,0]
	v_pk_fma_f32 v[40:41], v[178:179], v[30:31], v[196:197] neg_lo:[1,0,0] neg_hi:[1,0,0]
	v_mov_b32_e32 v197, v37
	v_mov_b32_e32 v196, v41
	v_mov_b32_e32 v30, v40
	v_mov_b32_e32 v31, v36
	v_pk_mul_f32 v[196:197], v[196:197], v[196:197]
	v_pk_fma_f32 v[34:35], v[178:179], v[222:223], v[34:35] neg_lo:[1,0,0] neg_hi:[1,0,0]
	v_pk_fma_f32 v[196:197], v[30:31], v[30:31], v[196:197]
	v_pk_mul_f32 v[30:31], v[86:87], v[20:21] op_sel_hi:[1,0]
	v_mov_b32_e32 v222, v34
	v_pk_fma_f32 v[30:31], v[178:179], v[30:31], v[224:225] neg_lo:[1,0,0] neg_hi:[1,0,0]
	v_mov_b32_e32 v224, v35
	v_mov_b32_e32 v225, v31
	v_mov_b32_e32 v223, v30
	v_pk_mul_f32 v[224:225], v[224:225], v[224:225]
	v_add_f32_e32 v21, v232, v233
	v_pk_fma_f32 v[222:223], v[222:223], v[222:223], v[224:225]
	v_add_f32_e32 v224, v228, v229
	v_add_f32_e32 v173, v224, v173
	v_add_f32_e32 v21, v173, v21
	v_add_f32_e32 v173, v230, v231
	v_add_f32_e32 v21, v21, v173
	v_add_f32_e32 v173, v236, v237
	v_add_f32_e32 v21, v21, v173
	v_add_f32_e32 v173, v234, v235
	v_add_f32_e32 v21, v21, v173
	v_add_f32_e32 v173, v240, v241
	v_add_f32_e32 v21, v21, v173
	v_add_f32_e32 v173, v238, v239
	v_add_f32_e32 v21, v21, v173
	v_add_f32_e32 v173, v244, v245
	v_add_f32_e32 v21, v21, v173
	v_add_f32_e32 v173, v242, v243
	v_add_f32_e32 v21, v21, v173
	v_add_f32_e32 v173, v248, v249
	v_add_f32_e32 v21, v21, v173
	v_add_f32_e32 v173, v246, v247
	v_add_f32_e32 v21, v21, v173
	v_add_f32_e32 v173, v252, v253
	v_add_f32_e32 v21, v21, v173
	v_add_f32_e32 v173, v250, v251
	v_add_f32_e32 v21, v21, v173
	v_add_f32_e32 v21, v21, v156
	v_add_f32_e32 v156, v158, v159
	v_add_f32_e32 v21, v21, v156
	v_add_f32_e32 v156, v160, v161
	v_add_f32_e32 v21, v21, v156
	v_add_f32_e32 v156, v162, v163
	v_pk_mul_f32 v[166:167], v[48:49], v[48:49]
	v_add_f32_e32 v21, v21, v156
	v_add_f32_e32 v156, v164, v165
	v_pk_mul_f32 v[168:169], v[46:47], v[46:47]
	v_add_f32_e32 v21, v21, v156
	v_add_f32_e32 v156, v166, v167
	v_pk_mul_f32 v[170:171], v[44:45], v[44:45]
	v_add_f32_e32 v21, v21, v156
	v_add_f32_e32 v156, v168, v169
	v_add_f32_e32 v21, v21, v156
	v_add_f32_e32 v156, v170, v171
	v_add_f32_e32 v21, v21, v156
	v_add_f32_e32 v21, v21, v192
	v_add_f32_e32 v21, v21, v193
	v_add_f32_e32 v21, v21, v196
	v_add_f32_e32 v21, v21, v197
	v_add_f32_e32 v21, v21, v222
	v_add_f32_e32 v21, v21, v223
	v_add_f32_e32 v21, v21, v32
	v_add_f32_e32 v21, v21, v33
	v_add_f32_e32 v21, v21, v150
	v_add_f32_e32 v21, v21, v151
	ds_bpermute_b32 v32, v221, v21
	s_mov_b32 s6, 0x800000
	global_load_dwordx2 v[80:81], v[188:189], off offset:16
	global_load_dwordx4 v[112:115], v[186:187], off offset:32
	global_load_dwordx4 v[116:119], v[186:187], off offset:64
	global_load_dwordx2 v[82:83], v[188:189], off offset:32
	global_load_dwordx2 v[84:85], v[188:189], off offset:48
	global_load_dwordx4 v[120:123], v[186:187], off offset:96
	global_load_dwordx4 v[124:127], v[186:187], off offset:128
	global_load_dwordx2 v[86:87], v[188:189], off offset:64
	global_load_dwordx2 v[88:89], v[188:189], off offset:80
	global_load_dwordx4 v[128:131], v[186:187], off offset:160
	global_load_dwordx4 v[132:135], v[186:187], off offset:192
	global_load_dwordx2 v[90:91], v[188:189], off offset:96
	global_load_dwordx2 v[92:93], v[188:189], off offset:112
	global_load_dwordx4 v[136:139], v[186:187], off offset:224
	global_load_dwordx4 v[140:143], v[186:187], off offset:256
	global_load_dwordx2 v[94:95], v[188:189], off offset:128
	global_load_dwordx2 v[96:97], v[188:189], off offset:144
	global_load_dwordx4 v[158:161], v[186:187], off offset:288
	global_load_dwordx4 v[162:165], v[186:187], off offset:320
	global_load_dwordx2 v[98:99], v[188:189], off offset:160
	global_load_dwordx2 v[100:101], v[188:189], off offset:176
	global_load_dwordx4 v[166:169], v[186:187], off offset:352
	global_load_dwordx4 v[108:111], v[186:187], off offset:384
	global_load_dwordx2 v[102:103], v[188:189], off offset:192
	global_load_dwordx2 v[104:105], v[188:189], off offset:208
	global_load_dwordx2 v[106:107], v[188:189], off offset:224
	global_load_dwordx2 v[170:171], v[188:189], off offset:240
	s_waitcnt vmcnt(27)
	v_lshlrev_b32_e32 v156, 16, v78
	v_and_b32_e32 v157, 0xffff0000, v78
	v_lshlrev_b32_e32 v78, 16, v79
	s_waitcnt lgkmcnt(0)
	v_add_f32_e32 v21, v21, v32
	v_fmamk_f32 v21, v21, 0x3c000000, v195
	v_mul_f32_e32 v32, 0x4b800000, v21
	v_cmp_gt_f32_e32 vcc, s6, v21
	v_and_b32_e32 v79, 0xffff0000, v79
	v_cndmask_b32_e32 v21, v21, v32, vcc
	v_rsq_f32_e32 v21, v21
	s_nop 0
	v_mul_f32_e32 v32, 0x45800000, v21
	v_cndmask_b32_e32 v21, v21, v32, vcc
	v_mul_f32_e32 v32, v207, v21
	v_pk_mul_f32 v[148:149], v[148:149], v[32:33] op_sel_hi:[1,0]
	v_pk_mul_f32 v[76:77], v[76:77], v[32:33] op_sel_hi:[1,0]
	v_pk_mul_f32 v[16:17], v[16:17], v[148:149]
	v_pk_mul_f32 v[18:19], v[18:19], v[76:77]
	v_pk_mul_f32 v[16:17], v[16:17], v[156:157]
	v_pk_mul_f32 v[18:19], v[18:19], v[78:79]
	v_cvt_pk_bf16_f32 v16, v16, v17
	v_cvt_pk_bf16_f32 v17, v18, v19
	global_store_dwordx2 v[190:191], v[16:17], off
	v_pk_mul_f32 v[148:149], v[152:153], v[32:33] op_sel_hi:[1,0]
	v_pk_mul_f32 v[74:75], v[74:75], v[32:33] op_sel_hi:[1,0]
	v_pk_mul_f32 v[72:73], v[72:73], v[32:33] op_sel_hi:[1,0]
	v_pk_mul_f32 v[70:71], v[70:71], v[32:33] op_sel_hi:[1,0]
	v_pk_mul_f32 v[68:69], v[68:69], v[32:33] op_sel_hi:[1,0]
	v_pk_mul_f32 v[66:67], v[66:67], v[32:33] op_sel_hi:[1,0]
	v_pk_mul_f32 v[64:65], v[64:65], v[32:33] op_sel_hi:[1,0]
	v_pk_mul_f32 v[62:63], v[62:63], v[32:33] op_sel_hi:[1,0]
	v_pk_mul_f32 v[60:61], v[60:61], v[32:33] op_sel_hi:[1,0]
	v_pk_mul_f32 v[58:59], v[58:59], v[32:33] op_sel_hi:[1,0]
	v_pk_mul_f32 v[56:57], v[56:57], v[32:33] op_sel_hi:[1,0]
	v_pk_mul_f32 v[54:55], v[54:55], v[32:33] op_sel_hi:[1,0]
	v_pk_mul_f32 v[52:53], v[52:53], v[32:33] op_sel_hi:[1,0]
	v_pk_mul_f32 v[50:51], v[50:51], v[32:33] op_sel_hi:[1,0]
	v_pk_mul_f32 v[48:49], v[48:49], v[32:33] op_sel_hi:[1,0]
	v_pk_mul_f32 v[46:47], v[46:47], v[32:33] op_sel_hi:[1,0]
	v_pk_mul_f32 v[44:45], v[44:45], v[32:33] op_sel_hi:[1,0]
	v_pk_mul_f32 v[42:43], v[42:43], v[32:33] op_sel_hi:[1,0]
	v_pk_mul_f32 v[38:39], v[38:39], v[32:33] op_sel_hi:[1,0]
	v_pk_mul_f32 v[40:41], v[40:41], v[32:33] op_sel_hi:[1,0]
	v_pk_mul_f32 v[36:37], v[36:37], v[32:33] op_sel_hi:[1,0]
	v_pk_mul_f32 v[34:35], v[34:35], v[32:33] op_sel_hi:[1,0]
	v_pk_mul_f32 v[30:31], v[30:31], v[32:33] op_sel_hi:[1,0]
	s_waitcnt vmcnt(27)
	v_lshlrev_b32_e32 v76, 16, v80
	v_and_b32_e32 v77, 0xffff0000, v80
	v_lshlrev_b32_e32 v78, 16, v81
	v_and_b32_e32 v79, 0xffff0000, v81
	s_waitcnt vmcnt(26)
	v_pk_mul_f32 v[16:17], v[112:113], v[148:149]
	s_nop 0
	v_pk_mul_f32 v[16:17], v[16:17], v[76:77]
	v_pk_mul_f32 v[76:77], v[146:147], v[32:33] op_sel_hi:[1,0]
	v_cvt_pk_bf16_f32 v16, v16, v17
	v_pk_mul_f32 v[18:19], v[114:115], v[76:77]
	s_nop 0
	v_pk_mul_f32 v[18:19], v[18:19], v[78:79]
	v_pk_mul_f32 v[78:79], v[154:155], v[32:33] op_sel_hi:[1,0]
	v_cvt_pk_bf16_f32 v17, v18, v19
	global_store_dwordx2 v[190:191], v[16:17], off offset:16
	s_waitcnt vmcnt(26)
	v_pk_mul_f32 v[16:17], v[116:117], v[78:79]
	s_waitcnt vmcnt(25)
	v_lshlrev_b32_e32 v146, 16, v82
	v_and_b32_e32 v147, 0xffff0000, v82
	v_pk_mul_f32 v[18:19], v[118:119], v[74:75]
	v_lshlrev_b32_e32 v74, 16, v83
	v_and_b32_e32 v75, 0xffff0000, v83
	v_pk_mul_f32 v[16:17], v[16:17], v[146:147]
	v_pk_mul_f32 v[18:19], v[18:19], v[74:75]
	v_cvt_pk_bf16_f32 v16, v16, v17
	v_cvt_pk_bf16_f32 v17, v18, v19
	global_store_dwordx2 v[190:191], v[16:17], off offset:32
	v_pk_mul_f32 v[74:75], v[144:145], v[32:33] op_sel_hi:[1,0]
	s_waitcnt vmcnt(25)
	v_lshlrev_b32_e32 v76, 16, v84
	v_and_b32_e32 v77, 0xffff0000, v84
	v_lshlrev_b32_e32 v78, 16, v85
	v_and_b32_e32 v79, 0xffff0000, v85
	s_waitcnt vmcnt(24)
	v_pk_mul_f32 v[16:17], v[120:121], v[74:75]
	v_pk_mul_f32 v[18:19], v[122:123], v[72:73]
	v_pk_mul_f32 v[16:17], v[16:17], v[76:77]
	v_pk_mul_f32 v[18:19], v[18:19], v[78:79]
	v_cvt_pk_bf16_f32 v16, v16, v17
	v_cvt_pk_bf16_f32 v17, v18, v19
	global_store_dwordx2 v[190:191], v[16:17], off offset:48
	s_waitcnt vmcnt(24)
	v_pk_mul_f32 v[16:17], v[70:71], v[124:125]
	s_waitcnt vmcnt(23)
	v_lshlrev_b32_e32 v70, 16, v86
	v_and_b32_e32 v71, 0xffff0000, v86
	v_pk_mul_f32 v[18:19], v[68:69], v[126:127]
	v_lshlrev_b32_e32 v68, 16, v87
	v_and_b32_e32 v69, 0xffff0000, v87
	v_pk_mul_f32 v[16:17], v[16:17], v[70:71]
	v_pk_mul_f32 v[18:19], v[18:19], v[68:69]
	v_cvt_pk_bf16_f32 v16, v16, v17
	v_cvt_pk_bf16_f32 v17, v18, v19
	global_store_dwordx2 v[190:191], v[16:17], off offset:64
	s_waitcnt vmcnt(23)
	v_lshlrev_b32_e32 v68, 16, v88
	v_and_b32_e32 v69, 0xffff0000, v88
	v_lshlrev_b32_e32 v70, 16, v89
	v_and_b32_e32 v71, 0xffff0000, v89
	s_waitcnt vmcnt(22)
	v_pk_mul_f32 v[16:17], v[66:67], v[128:129]
	v_pk_mul_f32 v[18:19], v[64:65], v[130:131]
	v_pk_mul_f32 v[16:17], v[16:17], v[68:69]
	v_pk_mul_f32 v[18:19], v[18:19], v[70:71]
	v_cvt_pk_bf16_f32 v16, v16, v17
	v_cvt_pk_bf16_f32 v17, v18, v19
	global_store_dwordx2 v[190:191], v[16:17], off offset:80
	s_waitcnt vmcnt(22)
	v_pk_mul_f32 v[16:17], v[62:63], v[132:133]
	s_waitcnt vmcnt(21)
	v_lshlrev_b32_e32 v62, 16, v90
	v_and_b32_e32 v63, 0xffff0000, v90
	v_pk_mul_f32 v[18:19], v[60:61], v[134:135]
	v_lshlrev_b32_e32 v60, 16, v91
	v_and_b32_e32 v61, 0xffff0000, v91
	v_pk_mul_f32 v[16:17], v[16:17], v[62:63]
	v_pk_mul_f32 v[18:19], v[18:19], v[60:61]
	v_cvt_pk_bf16_f32 v16, v16, v17
	v_cvt_pk_bf16_f32 v17, v18, v19
	global_store_dwordx2 v[190:191], v[16:17], off offset:96
	s_waitcnt vmcnt(21)
	v_lshlrev_b32_e32 v60, 16, v92
	v_and_b32_e32 v61, 0xffff0000, v92
	v_lshlrev_b32_e32 v62, 16, v93
	v_and_b32_e32 v63, 0xffff0000, v93
	s_waitcnt vmcnt(20)
	v_pk_mul_f32 v[16:17], v[58:59], v[136:137]
	v_pk_mul_f32 v[18:19], v[56:57], v[138:139]
	v_pk_mul_f32 v[16:17], v[16:17], v[60:61]
	v_pk_mul_f32 v[18:19], v[18:19], v[62:63]
	v_cvt_pk_bf16_f32 v16, v16, v17
	v_cvt_pk_bf16_f32 v17, v18, v19
	global_store_dwordx2 v[190:191], v[16:17], off offset:112
	s_waitcnt vmcnt(20)
	v_pk_mul_f32 v[16:17], v[54:55], v[140:141]
	s_waitcnt vmcnt(19)
	v_lshlrev_b32_e32 v54, 16, v94
	v_and_b32_e32 v55, 0xffff0000, v94
	v_pk_mul_f32 v[18:19], v[52:53], v[142:143]
	v_lshlrev_b32_e32 v52, 16, v95
	v_and_b32_e32 v53, 0xffff0000, v95
	v_pk_mul_f32 v[16:17], v[16:17], v[54:55]
	v_pk_mul_f32 v[18:19], v[18:19], v[52:53]
	v_cvt_pk_bf16_f32 v16, v16, v17
	v_cvt_pk_bf16_f32 v17, v18, v19
	global_store_dwordx2 v[190:191], v[16:17], off offset:128
	s_waitcnt vmcnt(19)
	v_lshlrev_b32_e32 v52, 16, v96
	v_and_b32_e32 v53, 0xffff0000, v96
	v_lshlrev_b32_e32 v54, 16, v97
	v_and_b32_e32 v55, 0xffff0000, v97
	s_waitcnt vmcnt(18)
	v_pk_mul_f32 v[16:17], v[50:51], v[158:159]
	v_pk_mul_f32 v[18:19], v[48:49], v[160:161]
	v_pk_mul_f32 v[16:17], v[16:17], v[52:53]
	v_pk_mul_f32 v[18:19], v[18:19], v[54:55]
	v_cvt_pk_bf16_f32 v16, v16, v17
	v_cvt_pk_bf16_f32 v17, v18, v19
	global_store_dwordx2 v[190:191], v[16:17], off offset:144
	s_waitcnt vmcnt(18)
	v_pk_mul_f32 v[16:17], v[46:47], v[162:163]
	s_waitcnt vmcnt(17)
	v_lshlrev_b32_e32 v46, 16, v98
	v_and_b32_e32 v47, 0xffff0000, v98
	v_pk_mul_f32 v[18:19], v[44:45], v[164:165]
	v_lshlrev_b32_e32 v44, 16, v99
	v_and_b32_e32 v45, 0xffff0000, v99
	v_pk_mul_f32 v[16:17], v[16:17], v[46:47]
	v_pk_mul_f32 v[18:19], v[18:19], v[44:45]
	v_cvt_pk_bf16_f32 v16, v16, v17
	v_cvt_pk_bf16_f32 v17, v18, v19
	global_store_dwordx2 v[190:191], v[16:17], off offset:160
	s_waitcnt vmcnt(17)
	v_lshlrev_b32_e32 v44, 16, v100
	v_and_b32_e32 v45, 0xffff0000, v100
	v_lshlrev_b32_e32 v46, 16, v101
	v_and_b32_e32 v47, 0xffff0000, v101
	s_waitcnt vmcnt(16)
	v_pk_mul_f32 v[16:17], v[42:43], v[166:167]
	v_pk_mul_f32 v[18:19], v[38:39], v[168:169]
	v_pk_mul_f32 v[16:17], v[16:17], v[44:45]
	v_pk_mul_f32 v[18:19], v[18:19], v[46:47]
	v_cvt_pk_bf16_f32 v16, v16, v17
	v_cvt_pk_bf16_f32 v17, v18, v19
	global_store_dwordx2 v[190:191], v[16:17], off offset:176
	s_waitcnt vmcnt(16)
	v_pk_mul_f32 v[16:17], v[40:41], v[108:109]
	s_waitcnt vmcnt(15)
	v_lshlrev_b32_e32 v40, 16, v102
	v_and_b32_e32 v41, 0xffff0000, v102
	v_pk_mul_f32 v[18:19], v[36:37], v[110:111]
	v_lshlrev_b32_e32 v36, 16, v103
	v_and_b32_e32 v37, 0xffff0000, v103
	v_pk_mul_f32 v[16:17], v[16:17], v[40:41]
	v_pk_mul_f32 v[18:19], v[18:19], v[36:37]
	v_cvt_pk_bf16_f32 v16, v16, v17
	v_cvt_pk_bf16_f32 v17, v18, v19
	global_store_dwordx2 v[190:191], v[16:17], off offset:192
	global_load_dwordx4 v[16:19], v[186:187], off offset:416
	s_waitcnt vmcnt(16)
	v_lshlrev_b32_e32 v36, 16, v104
	v_and_b32_e32 v37, 0xffff0000, v104
	v_lshlrev_b32_e32 v38, 16, v105
	v_and_b32_e32 v39, 0xffff0000, v105
	s_waitcnt vmcnt(0)
	v_pk_mul_f32 v[16:17], v[34:35], v[16:17]
	v_pk_mul_f32 v[18:19], v[30:31], v[18:19]
	v_pk_mul_f32 v[16:17], v[16:17], v[36:37]
	v_pk_mul_f32 v[18:19], v[18:19], v[38:39]
	v_cvt_pk_bf16_f32 v16, v16, v17
	v_cvt_pk_bf16_f32 v17, v18, v19
	global_store_dwordx2 v[190:191], v[16:17], off offset:208
	global_load_dwordx4 v[16:19], v[186:187], off offset:448
	v_mov_b32_e32 v34, v26
	v_mov_b32_e32 v35, v28
	v_mov_b32_e32 v28, v27
	v_pk_mul_f32 v[26:27], v[34:35], v[32:33] op_sel_hi:[1,0]
	v_pk_mul_f32 v[28:29], v[28:29], v[32:33] op_sel_hi:[1,0]
	s_waitcnt vmcnt(0)
	v_pk_mul_f32 v[16:17], v[26:27], v[16:17]
	v_lshlrev_b32_e32 v26, 16, v106
	v_and_b32_e32 v27, 0xffff0000, v106
	v_pk_mul_f32 v[18:19], v[28:29], v[18:19]
	v_lshlrev_b32_e32 v28, 16, v107
	v_and_b32_e32 v29, 0xffff0000, v107
	v_pk_mul_f32 v[16:17], v[16:17], v[26:27]
	v_pk_mul_f32 v[18:19], v[18:19], v[28:29]
	v_cvt_pk_bf16_f32 v16, v16, v17
	v_cvt_pk_bf16_f32 v17, v18, v19
	global_store_dwordx2 v[190:191], v[16:17], off offset:224
	global_load_dwordx4 v[16:19], v[186:187], off offset:480
	v_mov_b32_e32 v26, v22
	v_mov_b32_e32 v27, v24
	v_mov_b32_e32 v24, v23
	v_pk_mul_f32 v[22:23], v[26:27], v[32:33] op_sel_hi:[1,0]
	v_pk_mul_f32 v[24:25], v[24:25], v[32:33] op_sel_hi:[1,0]
	v_lshlrev_b32_e32 v26, 16, v170
	v_and_b32_e32 v27, 0xffff0000, v170
	v_lshlrev_b32_e32 v28, 16, v171
	v_and_b32_e32 v29, 0xffff0000, v171
	s_waitcnt vmcnt(0)
	v_pk_mul_f32 v[16:17], v[22:23], v[16:17]
	v_pk_mul_f32 v[18:19], v[24:25], v[18:19]
	v_pk_mul_f32 v[16:17], v[16:17], v[26:27]
	v_pk_mul_f32 v[18:19], v[18:19], v[28:29]
	v_cvt_pk_bf16_f32 v16, v16, v17
	v_cvt_pk_bf16_f32 v17, v18, v19
	global_store_dwordx2 v[190:191], v[16:17], off offset:240
	s_cbranch_execnz .LBB0_532
	s_branch .LBB0_565
